# speedup vs baseline: 1.0042x; 1.0042x over previous
; __device__ __forceinline__ void sb_phase(const Params& p, char* shm, int wv, int vb) {
;   const int tid = opaque_tid(wv), w = tid >> 6, lane = tid & 63, fr = lane & 15, fq = lane >> 4;
;   const int srow = tid >> 3, sch = tid & 7;
;   const int sdst = srow * 144 + sch * 16;
;   int* flags = (int*)(shm + SB_NPRE * SB_SLOT);
;     ...
;   int idx = vb;
;   asm volatile("" : "+s"(idx));
;   if (idx < 1024) {
;     SB_FETCH(idx);
;     SB_COMMIT();
;   }
;   __syncthreads();
;   for (; idx < 1024; idx += nblk) {
.LBB0_331:
	s_waitcnt lgkmcnt(0)
	v_mbcnt_lo_u32_b32 v0, -1, 0
	v_mbcnt_hi_u32_b32 v0, -1, v0
	s_movk_i32 s0, 0x90
	v_add_u32_e32 v68, s84, v0
	s_cmpk_ge_u32 s84, 0x100
	s_cbranch_scc0 .Lattn_prio_skip
	s_setprio 1
.Lattn_prio_skip:
	v_readlane_b32 s8, v254, 10
	v_ashrrev_i32_e32 v162, 3, v68
	v_and_b32_e32 v3, 7, v68
	v_mul_lo_u32 v0, v162, s0
	s_cmpk_lt_i32 s8, 0x400
	v_mov_b32_e32 v247, 1
	s_cselect_b64 s[0:1], -1, 0
	s_cmpk_gt_i32 s8, 0x3ff
	v_lshl_add_u32 v185, v3, 4, v0
	s_cbranch_scc1 .LBB0_355
	s_mov_b64 s[2:3], -1
	s_and_b64 vcc, exec, s[66:67]
	s_cbranch_vccz .LBB0_338
	s_ashr_i32 s4, s8, 8
	s_bfe_u32 s5, s8, 0x20006
	s_bitcmp0_b32 s8, 8
	s_cbranch_scc1 .LBB0_335
	s_lshl_b32 s2, s4, 2
	s_sub_i32 s2, s5, s2
	s_add_i32 s9, s2, 12
	s_mov_b64 s[2:3], 0

;   __device__ __forceinline__ unsigned* bar() const { return (unsigned*)(ws + 501 * MB); }
; __device__ __forceinline__ unsigned xb_ld(unsigned* p) { return __hip_atomic_load(p, __ATOMIC_RELAXED, __HIP_MEMORY_SCOPE_AGENT); }
; __device__ __forceinline__ unsigned xb_add(unsigned* p, unsigned v) { return __hip_atomic_fetch_add(p, v, __ATOMIC_RELAXED, __HIP_MEMORY_SCOPE_AGENT); }
; #define XB_SPIN(cond, bar) do { unsigned _sp = 0; while (cond) { __builtin_amdgcn_s_sleep(1); \
;     if ((++_sp & 255u) == 0u) { if (xb_ld(&(bar)[XB_TMO])) break; if (_sp > XB_SPIN_CAP) { atomicAdd(&(bar)[XB_TMO], 1u); break; } } } } while (0)
; __device__ __forceinline__ void xcd_barrier_local(XcdBarrier& b, int wv) {
;   asm volatile("s_waitcnt vmcnt(0)" ::: "memory");
;   __syncthreads();
;   if (opaque_tid(wv) == 0) {
;     unsigned* bar = b.bar;
;     unsigned x = b.x, nloc = b.nloc, gen = b.seql;
;     asm volatile("" : "+s"(bar), "+s"(x), "+s"(nloc), "+s"(gen));
;     __builtin_amdgcn_s_waitcnt(0);
;     const unsigned old = xb_add(&bar[XB_LSUB(x)], 1u);
;     if (old + 1u == (gen + 1u) * nloc) {
;       __builtin_amdgcn_fence(__ATOMIC_ACQUIRE, "agent");
;       xb_add(&bar[XB_LGEN(x)], 1u);
;     } else {
;       XB_SPIN(xb_ld(&bar[XB_LGEN(x)]) == gen, bar);
;       __builtin_amdgcn_fence(__ATOMIC_ACQUIRE, "agent");
;     }
;   }
;   b.seql += 1u;
;   __syncthreads();
; }
.LBB0_444:
	s_setprio 0
	v_readlane_b32 s2, v254, 32
	v_readlane_b32 s3, v254, 33
	s_mov_b64 s[0:1], -1
	s_and_b64 vcc, exec, s[2:3]
	s_cbranch_vccz .LBB0_462
	s_waitcnt vmcnt(0)
	s_barrier
	v_mbcnt_lo_u32_b32 v0, -1, 0
	v_mbcnt_hi_u32_b32 v0, -1, v0
	s_nop 0
	v_add_u32_e32 v0, s84, v0
	s_nop 0
	v_cmp_eq_u32_e32 vcc, 0, v0
	s_and_saveexec_b64 s[0:1], vcc
	s_cbranch_execz .LBB0_461
	v_readlane_b32 s2, v254, 6
	v_readlane_b32 s3, v254, 7
	v_readlane_b32 s6, v254, 9
	v_readlane_b32 s4, v254, 8
	v_readlane_b32 s53, v255, 22
	s_lshl_b32 s51, s4, 6
	s_add_i32 s4, s51, 0xdc0
	s_mov_b32 s5, s52
	s_lshl_b64 s[4:5], s[4:5], 2
	s_add_u32 s4, s2, s4
	s_addc_u32 s5, s3, s5
	v_mov_b64_e32 v[0:1], s[4:5]
	s_waitcnt vmcnt(0) expcnt(0) lgkmcnt(0)
	flat_atomic_add v0, v[0:1], v185 sc0
	s_add_i32 s4, s53, 1
	s_mul_i32 s4, s4, s6
	s_waitcnt vmcnt(0) lgkmcnt(0)
	v_add_u32_e32 v0, 1, v0
	v_cmp_ne_u32_e32 vcc, s4, v0
	s_and_saveexec_b64 s[4:5], vcc
	s_xor_b64 s[4:5], exec, s[4:5]
	s_cbranch_execz .LBB0_459
	s_add_i32 s6, s51, 0x11c0
	s_mov_b32 s7, s52
	s_lshl_b64 s[6:7], s[6:7], 2
	s_add_u32 s8, s2, s6
	s_addc_u32 s9, s3, s7
	v_mov_b64_e32 v[0:1], s[8:9]
	flat_load_dword v0, v[0:1] sc1
	s_waitcnt vmcnt(0) lgkmcnt(0)
	v_cmp_eq_u32_e32 vcc, s53, v0
	s_and_saveexec_b64 s[6:7], vcc
	s_cbranch_execz .LBB0_458
	s_mov_b32 s54, 1
	s_mov_b64 s[10:11], 0
	s_branch .LBB0_450
